# diff unit epilogue: 16 dwordx2 row-fragment stores widened to 8 dwordx4 via v_permlane32_swap (T21)
# speedup vs baseline: 1.0041x; 1.0034x over previous
; __device__ __forceinline__ unsigned pk2(float lo, float hi) { f32x2 v = {lo, hi}; bf16x2_t b = __builtin_convertvector(v, bf16x2_t); return __builtin_bit_cast(unsigned, b); }
; __device__ __forceinline__ float shfl_xor_l(float v, int o, int lane) { return __builtin_bit_cast(float, __builtin_amdgcn_ds_bpermute((lane ^ o) << 2, __builtin_bit_cast(int, v))); }
; template <int DQK, int DV, int FLAGS, int qp, int kp, int vts, int op> ...
;     ...
;     float lt = l + shfl_xor_l(l, 32, lane);
;     if (FLAGS & AF_SINK) lt += __builtin_amdgcn_exp2f(sink2 - m);
;     const float inv = 1.0f / lt;
;     bf16* orow = O + (size_t)(32 * wave + r32) * op + 4 * hi;
; #pragma unroll
;     for (int d = 0; d < NDB; ++d)
; #pragma unroll
;         for (int g = 0; g < 4; ++g) {
;             u32x2 w; w.x = pk2(o[d][4 * g] * inv, o[d][4 * g + 1] * inv); w.y = pk2(o[d][4 * g + 2] * inv, o[d][4 * g + 3] * inv);
;             *(u32x2*)(orow + 32 * d + 8 * g) = w;
;         }
; __global__ void __launch_bounds__(NTHREADS, 2) mega_fwd(Args args) {
;     ...
;                     if (threadIdx.x == 0) *qslot = __hip_atomic_fetch_add(qctr, 1u, __ATOMIC_RELAXED, __HIP_MEMORY_SCOPE_AGENT);
.LBB0_924:
	s_mov_b64 s[98:99], exec
	v_readlane_b32 s100, v252, 4
	v_readlane_b32 s101, v252, 5
	s_nop 3
	s_mov_b64 exec, s[100:101]
	v_readlane_b32 s100, v254, 16
	v_readlane_b32 s101, v254, 17
	v_mov_b32_e32 v237, 1
	v_mov_b32_e32 v238, 0
	s_nop 4
	global_atomic_add v236, v238, v237, s[100:101] sc0
	s_mov_b64 exec, s[98:99]
	ds_bpermute_b32 v0, v80, v199
	s_cmp_eq_u32 s4, 0
	s_mov_b32 s2, 0x8200000
	v_readlane_b32 s8, v252, 0
	s_cselect_b32 s2, s2, 0xc200000
	v_readlane_b32 s10, v252, 2
	v_readlane_b32 s11, v252, 3
	s_add_u32 s2, s10, s2
	s_addc_u32 s4, s11, 0
	s_waitcnt lgkmcnt(0)
	v_add_f32_e32 v0, v199, v0
	s_add_u32 s6, s2, s30
	s_waitcnt vmcnt(3)
	v_div_scale_f32 v4, s[2:3], v0, v0, 1.0
	v_rcp_f32_e32 v5, v4
	s_addc_u32 s3, s4, s31
	s_add_u32 s2, s6, s5
	v_lshlrev_b64 v[2:3], 10, v[176:177]
	s_waitcnt vmcnt(2)
	v_fma_f32 v6, -v4, v5, 1.0
	v_fmac_f32_e32 v5, v6, v5
	v_div_scale_f32 v6, vcc, 1.0, v0, 1.0
	v_mul_f32_e32 v7, v6, v5
	v_fma_f32 v8, -v4, v7, v6
	v_fmac_f32_e32 v7, v8, v5
	v_fma_f32 v4, -v4, v7, v6
	v_div_fmas_f32 v4, v4, v5, v7
	s_addc_u32 s3, s3, 0
	v_div_fixup_f32 v0, v4, v0, 1.0
	v_lshl_add_u64 v[2:3], v[2:3], 1, s[2:3]
	v_mov_b32_e32 v199, v1
	v_lshl_add_u64 v[2:3], v[2:3], 0, v[198:199]
	v_lshl_add_u64 v[2:3], v[2:3], 0, v[198:199]
	v_pk_mul_f32 v[4:5], v[64:65], v[0:1] op_sel_hi:[1,0]
	v_pk_mul_f32 v[6:7], v[66:67], v[0:1] op_sel_hi:[1,0]
	v_pk_mul_f32 v[240:241], v[68:69], v[0:1] op_sel_hi:[1,0]
	v_pk_mul_f32 v[242:243], v[70:71], v[0:1] op_sel_hi:[1,0]
	v_cvt_pk_bf16_f32 v4, v4, v5
	v_cvt_pk_bf16_f32 v5, v6, v7
	v_cvt_pk_bf16_f32 v6, v240, v241
	v_cvt_pk_bf16_f32 v7, v242, v243
	s_nop 1
	v_permlane32_swap_b32 v4, v6
	v_permlane32_swap_b32 v5, v7
	global_store_dwordx4 v[2:3], v[4:7], off
	s_nop 1
	v_pk_mul_f32 v[4:5], v[72:73], v[0:1] op_sel_hi:[1,0]
	v_pk_mul_f32 v[6:7], v[74:75], v[0:1] op_sel_hi:[1,0]
	v_pk_mul_f32 v[240:241], v[76:77], v[0:1] op_sel_hi:[1,0]
	v_pk_mul_f32 v[242:243], v[78:79], v[0:1] op_sel_hi:[1,0]
	v_cvt_pk_bf16_f32 v4, v4, v5
	v_cvt_pk_bf16_f32 v5, v6, v7
	v_cvt_pk_bf16_f32 v6, v240, v241
	v_cvt_pk_bf16_f32 v7, v242, v243
	s_nop 1
	v_permlane32_swap_b32 v4, v6
	v_permlane32_swap_b32 v5, v7
	global_store_dwordx4 v[2:3], v[4:7], off offset:32
	s_nop 1
	v_pk_mul_f32 v[4:5], v[48:49], v[0:1] op_sel_hi:[1,0]
	v_pk_mul_f32 v[6:7], v[50:51], v[0:1] op_sel_hi:[1,0]
	v_pk_mul_f32 v[240:241], v[52:53], v[0:1] op_sel_hi:[1,0]
	v_pk_mul_f32 v[242:243], v[54:55], v[0:1] op_sel_hi:[1,0]
	v_cvt_pk_bf16_f32 v4, v4, v5
	v_cvt_pk_bf16_f32 v5, v6, v7
	v_cvt_pk_bf16_f32 v6, v240, v241
	v_cvt_pk_bf16_f32 v7, v242, v243
	s_nop 1
	v_permlane32_swap_b32 v4, v6
	v_permlane32_swap_b32 v5, v7
	global_store_dwordx4 v[2:3], v[4:7], off offset:64
	s_nop 1
	v_pk_mul_f32 v[4:5], v[56:57], v[0:1] op_sel_hi:[1,0]
	v_pk_mul_f32 v[6:7], v[58:59], v[0:1] op_sel_hi:[1,0]
	v_pk_mul_f32 v[240:241], v[60:61], v[0:1] op_sel_hi:[1,0]
	v_pk_mul_f32 v[242:243], v[62:63], v[0:1] op_sel_hi:[1,0]
	v_cvt_pk_bf16_f32 v4, v4, v5
	v_cvt_pk_bf16_f32 v5, v6, v7
	v_cvt_pk_bf16_f32 v6, v240, v241
	v_cvt_pk_bf16_f32 v7, v242, v243
	s_nop 1
	v_permlane32_swap_b32 v4, v6
	v_permlane32_swap_b32 v5, v7
	global_store_dwordx4 v[2:3], v[4:7], off offset:96
	s_nop 1
	v_pk_mul_f32 v[4:5], v[32:33], v[0:1] op_sel_hi:[1,0]
	v_pk_mul_f32 v[6:7], v[34:35], v[0:1] op_sel_hi:[1,0]
	v_pk_mul_f32 v[240:241], v[36:37], v[0:1] op_sel_hi:[1,0]
	v_pk_mul_f32 v[242:243], v[38:39], v[0:1] op_sel_hi:[1,0]
	v_cvt_pk_bf16_f32 v4, v4, v5
	v_cvt_pk_bf16_f32 v5, v6, v7
	v_cvt_pk_bf16_f32 v6, v240, v241
	v_cvt_pk_bf16_f32 v7, v242, v243
	s_nop 1
	v_permlane32_swap_b32 v4, v6
	v_permlane32_swap_b32 v5, v7
	global_store_dwordx4 v[2:3], v[4:7], off offset:128
	s_nop 1
	v_pk_mul_f32 v[4:5], v[40:41], v[0:1] op_sel_hi:[1,0]
	v_pk_mul_f32 v[6:7], v[42:43], v[0:1] op_sel_hi:[1,0]
	v_pk_mul_f32 v[240:241], v[44:45], v[0:1] op_sel_hi:[1,0]
	v_pk_mul_f32 v[242:243], v[46:47], v[0:1] op_sel_hi:[1,0]
	v_cvt_pk_bf16_f32 v4, v4, v5
	v_cvt_pk_bf16_f32 v5, v6, v7
	v_cvt_pk_bf16_f32 v6, v240, v241
	v_cvt_pk_bf16_f32 v7, v242, v243
	s_nop 1
	v_permlane32_swap_b32 v4, v6
	v_permlane32_swap_b32 v5, v7
	global_store_dwordx4 v[2:3], v[4:7], off offset:160
	s_nop 1
	v_pk_mul_f32 v[4:5], v[16:17], v[0:1] op_sel_hi:[1,0]
	v_pk_mul_f32 v[6:7], v[18:19], v[0:1] op_sel_hi:[1,0]
	v_pk_mul_f32 v[240:241], v[20:21], v[0:1] op_sel_hi:[1,0]
	v_pk_mul_f32 v[242:243], v[22:23], v[0:1] op_sel_hi:[1,0]
	v_cvt_pk_bf16_f32 v4, v4, v5
	v_cvt_pk_bf16_f32 v5, v6, v7
	v_cvt_pk_bf16_f32 v6, v240, v241
	v_cvt_pk_bf16_f32 v7, v242, v243
	s_nop 1
	v_permlane32_swap_b32 v4, v6
	v_permlane32_swap_b32 v5, v7
	global_store_dwordx4 v[2:3], v[4:7], off offset:192
	s_nop 1
	v_pk_mul_f32 v[4:5], v[24:25], v[0:1] op_sel_hi:[1,0]
	v_pk_mul_f32 v[6:7], v[26:27], v[0:1] op_sel_hi:[1,0]
	v_pk_mul_f32 v[240:241], v[28:29], v[0:1] op_sel_hi:[1,0]
	v_pk_mul_f32 v[242:243], v[30:31], v[0:1] op_sel_hi:[1,0]
	v_cvt_pk_bf16_f32 v4, v4, v5
	v_cvt_pk_bf16_f32 v5, v6, v7
	v_cvt_pk_bf16_f32 v6, v240, v241
	v_cvt_pk_bf16_f32 v7, v242, v243
	s_nop 1
	v_permlane32_swap_b32 v4, v6
	v_permlane32_swap_b32 v5, v7
	global_store_dwordx4 v[2:3], v[4:7], off offset:224
	s_nop 1
	v_readlane_b32 s12, v255, 36
	s_mov_b64 s[6:7], 0
	v_readlane_b32 s9, v252, 1

; __global__ void __launch_bounds__(NTHREADS, 2) mega_fwd(Args args) {
;     ...
;                     if (threadIdx.x == 0) *qslot = __hip_atomic_fetch_add(qctr, 1u, __ATOMIC_RELAXED, __HIP_MEMORY_SCOPE_AGENT);
;                     __syncthreads();
.LBB0_926:
	s_mov_b64 s[6:7], exec
	v_readlane_b32 s2, v252, 4
	v_readlane_b32 s3, v252, 5
	s_and_b64 s[2:3], s[6:7], s[2:3]
	s_mov_b64 exec, s[2:3]
	s_cbranch_execz .LBB0_930
	s_waitcnt vmcnt(8)
	v_mov_b32_e32 v2, s12
	ds_write_b32 v2, v236
